# attention: lazy rescale triggered by the per-lane partial row sum (<= 8192) instead of a per-tile max chain; max is computed only on the rescale path; K fragments of a tile read in one burst
# speedup vs baseline: 1.0070x; 1.0070x over previous
; DI void attn_item(const Params& p, int item, char* smem) {
;     ...
;   auto tile_compute = [&](int cur) {
;     const u16* Kc = Ks + cur * 64 * KSL;
;     const u16* Vc = Vs + cur * 64 * VSL;
;     f32x16 p0, p1;
; #pragma unroll
;     for (int i = 0; i < 16; ++i) { p0[i] = 0.f; p1[i] = 0.f; }
; #pragma unroll
;     for (int d0 = 0; d0 < 6; ++d0) {
;       const bf16x8 a0 = *(const bf16x8*)(Kc + r32 * KSL + d0 * 16 + hi * 8);
;       const bf16x8 a1 = *(const bf16x8*)(Kc + (32 + r32) * KSL + d0 * 16 + hi * 8);
;       p0 = __builtin_amdgcn_mfma_f32_32x32x16_bf16(a0, qr[d0], p0, 0, 0, 0);
;       p1 = __builtin_amdgcn_mfma_f32_32x32x16_bf16(a1, qr[d0], p1, 0, 0, 0);
;     }
;     float mx = p0[0];
; #pragma unroll
;     for (int i = 1; i < 16; ++i) mx = fmaxf(mx, p0[i]);
; #pragma unroll
;     for (int i = 0; i < 16; ++i) mx = fmaxf(mx, p1[i]);
;     { auto rr = __builtin_amdgcn_permlane32_swap(__float_as_uint(mx), __float_as_uint(mx), false, false);
;       mx = fmaxf(__uint_as_float(rr[0]), __uint_as_float(rr[1])); }
;     if (!__all(mx - mrun <= 8.f)) {
;       const float mn = fmaxf(mrun, mx);
;       const float alpha = __builtin_amdgcn_exp2f(mrun - mn);
;       mrun = mn; lrun *= alpha;
; #pragma unroll
;       for (int i = 0; i < 16; ++i) { o0[i] *= alpha; o1[i] *= alpha; }
;     }
;     float ps = 0.f;
; #pragma unroll
;     for (int i = 0; i < 16; ++i) { p0[i] = __builtin_amdgcn_exp2f(p0[i] - mrun); ps += p0[i]; }
; #pragma unroll
;     for (int i = 0; i < 16; ++i) { p1[i] = __builtin_amdgcn_exp2f(p1[i] - mrun); ps += p1[i]; }
.LBB0_531:
	ds_read_b128 v[164:167], v154
	ds_read_b128 v[168:171], v154 offset:32
	ds_read_b128 v[172:175], v154 offset:64
	ds_read_b128 v[176:179], v154 offset:96
	ds_read_b128 v[180:183], v154 offset:128
	ds_read_b128 v[184:187], v154 offset:160
	ds_read_b128 v[188:191], v154 offset:6656
	ds_read_b128 v[158:161], v154 offset:6688
	ds_read_b128 v[192:195], v154 offset:6720
	ds_read_b128 v[212:215], v154 offset:6752
	ds_read_b128 v[216:219], v154 offset:6784
	ds_read_b128 v[10:13], v154 offset:6816
	s_waitcnt lgkmcnt(11)
	v_mfma_f32_32x32x16_bf16 v[64:79], v[164:167], v[80:83], v[196:211]
	s_waitcnt lgkmcnt(10)
	v_mfma_f32_32x32x16_bf16 v[64:79], v[168:171], v[84:87], v[64:79]
	s_waitcnt lgkmcnt(9)
	v_mfma_f32_32x32x16_bf16 v[64:79], v[172:175], v[88:91], v[64:79]
	s_waitcnt lgkmcnt(8)
	v_mfma_f32_32x32x16_bf16 v[64:79], v[176:179], v[92:95], v[64:79]
	s_waitcnt lgkmcnt(7)
	v_mfma_f32_32x32x16_bf16 v[64:79], v[180:183], v[96:99], v[64:79]
	s_waitcnt lgkmcnt(6)
	v_mfma_f32_32x32x16_bf16 v[64:79], v[184:187], v[100:103], v[64:79]
	s_waitcnt lgkmcnt(5)
	v_mfma_f32_32x32x16_bf16 v[48:63], v[188:191], v[80:83], v[196:211]
	s_waitcnt lgkmcnt(4)
	v_mfma_f32_32x32x16_bf16 v[48:63], v[158:161], v[84:87], v[48:63]
	s_nop 7
	v_exp_f32_e32 v168, v64
	v_exp_f32_e32 v169, v65
	v_exp_f32_e32 v170, v66
	v_exp_f32_e32 v171, v67
	v_exp_f32_e32 v172, v68
	v_exp_f32_e32 v173, v69
	v_exp_f32_e32 v174, v70
	v_exp_f32_e32 v175, v71
	s_waitcnt lgkmcnt(3)
	v_mfma_f32_32x32x16_bf16 v[48:63], v[192:195], v[88:91], v[48:63]
	s_waitcnt lgkmcnt(2)
	v_mfma_f32_32x32x16_bf16 v[48:63], v[212:215], v[92:95], v[48:63]
	v_exp_f32_e32 v176, v72
	v_exp_f32_e32 v177, v73
	v_exp_f32_e32 v178, v74
	v_exp_f32_e32 v179, v75
	v_exp_f32_e32 v180, v76
	v_exp_f32_e32 v181, v77
	v_exp_f32_e32 v182, v78
	v_exp_f32_e32 v183, v79
	s_waitcnt lgkmcnt(1)
	v_mfma_f32_32x32x16_bf16 v[48:63], v[216:219], v[96:99], v[48:63]
	s_waitcnt lgkmcnt(0)
	v_mfma_f32_32x32x16_bf16 v[48:63], v[10:13], v[100:103], v[48:63]
	v_add_f32_e32 v0, v168, v169
	v_add_f32_e32 v0, v170, v0
	v_add_f32_e32 v0, v171, v0
	v_add_f32_e32 v0, v172, v0
	v_add_f32_e32 v0, v173, v0
	v_add_f32_e32 v0, v174, v0
	v_add_f32_e32 v0, v175, v0
	v_add_f32_e32 v0, v176, v0
	v_add_f32_e32 v0, v177, v0
	v_add_f32_e32 v0, v178, v0
	v_add_f32_e32 v0, v179, v0
	v_add_f32_e32 v0, v180, v0
	v_add_f32_e32 v0, v181, v0
	v_add_f32_e32 v0, v182, v0
	v_add_f32_e32 v0, v183, v0
	v_exp_f32_e32 v184, v48
	v_exp_f32_e32 v185, v49
	v_exp_f32_e32 v186, v50
	v_exp_f32_e32 v187, v51
	v_exp_f32_e32 v188, v52
	v_exp_f32_e32 v189, v53
	v_exp_f32_e32 v190, v54
	v_exp_f32_e32 v191, v55
	v_exp_f32_e32 v158, v56
	v_exp_f32_e32 v159, v57
	v_exp_f32_e32 v160, v58
	v_exp_f32_e32 v161, v59
	v_exp_f32_e32 v164, v60
	v_exp_f32_e32 v165, v61
	v_exp_f32_e32 v166, v62
	v_exp_f32_e32 v167, v63
	v_add_f32_e32 v0, v184, v0
	v_add_f32_e32 v0, v185, v0
	v_add_f32_e32 v0, v186, v0
	v_add_f32_e32 v0, v187, v0
	v_add_f32_e32 v0, v188, v0
	v_add_f32_e32 v0, v189, v0
	v_add_f32_e32 v0, v190, v0
	v_add_f32_e32 v0, v191, v0
	v_add_f32_e32 v0, v158, v0
	v_add_f32_e32 v0, v159, v0
	v_add_f32_e32 v0, v160, v0
	v_add_f32_e32 v0, v161, v0
	v_add_f32_e32 v0, v164, v0
	v_add_f32_e32 v0, v165, v0
	v_add_f32_e32 v0, v166, v0
	v_add_f32_e32 v0, v167, v0
	v_cmp_ge_f32_e32 vcc, s98, v0
	s_cmp_eq_u64 vcc, exec
	s_cbranch_scc1 .LBB0_533
	v_max_f32_e32 v10, v64, v65
	v_max3_f32 v10, v10, v66, v67
	v_max3_f32 v10, v10, v68, v69
	v_max3_f32 v10, v10, v70, v71
	v_max3_f32 v10, v10, v72, v73
	v_max3_f32 v10, v10, v74, v75
	v_max3_f32 v10, v10, v76, v77
	v_max3_f32 v10, v10, v78, v79
	v_max3_f32 v10, v10, v48, v49
	v_max3_f32 v10, v10, v50, v51
	v_max3_f32 v10, v10, v52, v53
	v_max3_f32 v10, v10, v54, v55
	v_max3_f32 v10, v10, v56, v57
	v_max3_f32 v10, v10, v58, v59
	v_max3_f32 v10, v10, v60, v61
	v_max3_f32 v10, v10, v62, v63
	v_mov_b32_e32 v11, v10
	s_nop 1
	v_permlane32_swap_b32_e32 v10, v11
	v_max_f32_e32 v10, v10, v11
	v_max_f32_e32 v11, s99, v10
	v_max_f32_e32 v10, 0, v11
	s_mov_b32 s98, 0x46000000
	v_exp_f32_e64 v10, -v10
	s_mov_b32 s99, 0
	v_sub_f32_e32 v196, v196, v11
	v_mul_f32_e32 v157, v157, v10
	v_pk_mul_f32 v[46:47], v[46:47], v[10:11] op_sel_hi:[1,0]
	v_pk_mul_f32 v[44:45], v[44:45], v[10:11] op_sel_hi:[1,0]
	v_pk_mul_f32 v[42:43], v[42:43], v[10:11] op_sel_hi:[1,0]
	v_pk_mul_f32 v[40:41], v[40:41], v[10:11] op_sel_hi:[1,0]
	v_pk_mul_f32 v[38:39], v[38:39], v[10:11] op_sel_hi:[1,0]
	v_pk_mul_f32 v[36:37], v[36:37], v[10:11] op_sel_hi:[1,0]
	v_pk_mul_f32 v[34:35], v[34:35], v[10:11] op_sel_hi:[1,0]
	v_pk_mul_f32 v[32:33], v[32:33], v[10:11] op_sel_hi:[1,0]
	v_pk_mul_f32 v[30:31], v[30:31], v[10:11] op_sel_hi:[1,0]
	v_pk_mul_f32 v[28:29], v[28:29], v[10:11] op_sel_hi:[1,0]
	v_pk_mul_f32 v[26:27], v[26:27], v[10:11] op_sel_hi:[1,0]
	v_pk_mul_f32 v[24:25], v[24:25], v[10:11] op_sel_hi:[1,0]
	v_pk_mul_f32 v[22:23], v[22:23], v[10:11] op_sel_hi:[1,0]
	v_pk_mul_f32 v[20:21], v[20:21], v[10:11] op_sel_hi:[1,0]
	v_pk_mul_f32 v[18:19], v[18:19], v[10:11] op_sel_hi:[1,0]
	v_pk_mul_f32 v[16:17], v[16:17], v[10:11] op_sel_hi:[1,0]
	v_mov_b32_e32 v197, v196
	v_mov_b32_e32 v198, v196
	v_mov_b32_e32 v199, v196
	v_mov_b32_e32 v200, v196
	v_mov_b32_e32 v201, v196
	v_mov_b32_e32 v202, v196
	v_mov_b32_e32 v203, v196
	v_mov_b32_e32 v204, v196
	v_mov_b32_e32 v205, v196
	v_mov_b32_e32 v206, v196
	v_mov_b32_e32 v207, v196
	v_mov_b32_e32 v208, v196
	v_mov_b32_e32 v209, v196
	v_mov_b32_e32 v210, v196
	v_mov_b32_e32 v211, v196
	v_sub_f32_e32 v64, v64, v11
	v_sub_f32_e32 v65, v65, v11
	v_sub_f32_e32 v66, v66, v11
	v_sub_f32_e32 v67, v67, v11
	v_sub_f32_e32 v68, v68, v11
	v_sub_f32_e32 v69, v69, v11
; DI void attn_item(const Params& p, int item, char* smem) {
;     ...
;     if (!__all(mx - mrun <= 8.f)) {
;       const float mn = fmaxf(mrun, mx);
;       const float alpha = __builtin_amdgcn_exp2f(mrun - mn);
;       mrun = mn; lrun *= alpha;
; #pragma unroll
;       for (int i = 0; i < 16; ++i) { o0[i] *= alpha; o1[i] *= alpha; }
;     }
;     float ps = 0.f;
; #pragma unroll
;     for (int i = 0; i < 16; ++i) { p0[i] = __builtin_amdgcn_exp2f(p0[i] - mrun); ps += p0[i]; }
; #pragma unroll
;     for (int i = 0; i < 16; ++i) { p1[i] = __builtin_amdgcn_exp2f(p1[i] - mrun); ps += p1[i]; }
;     lrun += ps;
;     pv_step(o0, o1, Vc, r32, 0 + hi * 4, pack8<0>(p0));
;     pv_step(o0, o1, Vc, r32, 16 + hi * 4, pack8<8>(p0));
;     pv_step(o0, o1, Vc, r32, 32 + hi * 4, pack8<0>(p1));
;     pv_step(o0, o1, Vc, r32, 48 + hi * 4, pack8<8>(p1));
;     ...
;   for (int kt = 0; kt < nkt; kt += 2) {
;     if (kt + 2 < nkt) gload(b, kt + 2);
;     tile_compute(0);
;     lstore(a, 1);
;     __syncthreads();
;     if (kt + 3 < nkt) gload(a, kt + 3);
;     tile_compute(1);
;     if (kt + 2 < nkt) lstore(b, 0);
	v_sub_f32_e32 v70, v70, v11
	v_sub_f32_e32 v71, v71, v11
	v_sub_f32_e32 v72, v72, v11
	v_sub_f32_e32 v73, v73, v11
	v_sub_f32_e32 v74, v74, v11
	v_sub_f32_e32 v75, v75, v11
	v_sub_f32_e32 v76, v76, v11
	v_sub_f32_e32 v77, v77, v11
	v_sub_f32_e32 v78, v78, v11
	v_sub_f32_e32 v79, v79, v11
	v_sub_f32_e32 v48, v48, v11
	v_sub_f32_e32 v49, v49, v11
	v_sub_f32_e32 v50, v50, v11
	v_sub_f32_e32 v51, v51, v11
	v_sub_f32_e32 v52, v52, v11
	v_sub_f32_e32 v53, v53, v11
	v_sub_f32_e32 v54, v54, v11
	v_sub_f32_e32 v55, v55, v11
	v_sub_f32_e32 v56, v56, v11
	v_sub_f32_e32 v57, v57, v11
	v_sub_f32_e32 v58, v58, v11
	v_sub_f32_e32 v59, v59, v11
	v_sub_f32_e32 v60, v60, v11
	v_sub_f32_e32 v61, v61, v11
	v_sub_f32_e32 v62, v62, v11
	v_sub_f32_e32 v63, v63, v11
	v_exp_f32_e32 v168, v64
	v_exp_f32_e32 v169, v65
	v_exp_f32_e32 v170, v66
	v_exp_f32_e32 v171, v67
	v_exp_f32_e32 v172, v68
	v_exp_f32_e32 v173, v69
	v_exp_f32_e32 v174, v70
	v_exp_f32_e32 v175, v71
	v_exp_f32_e32 v176, v72
	v_exp_f32_e32 v177, v73
	v_exp_f32_e32 v178, v74
	v_exp_f32_e32 v179, v75
	v_exp_f32_e32 v180, v76
	v_exp_f32_e32 v181, v77
	v_exp_f32_e32 v182, v78
	v_exp_f32_e32 v183, v79
	v_exp_f32_e32 v184, v48
	v_exp_f32_e32 v185, v49
	v_exp_f32_e32 v186, v50
	v_exp_f32_e32 v187, v51
	v_exp_f32_e32 v188, v52
	v_exp_f32_e32 v189, v53
	v_exp_f32_e32 v190, v54
	v_exp_f32_e32 v191, v55
	v_exp_f32_e32 v158, v56
	v_exp_f32_e32 v159, v57
	v_exp_f32_e32 v160, v58
	v_exp_f32_e32 v161, v59
	v_exp_f32_e32 v164, v60
	v_exp_f32_e32 v165, v61
	v_exp_f32_e32 v166, v62
	v_exp_f32_e32 v167, v63
	v_add_f32_e32 v0, v168, v169
	v_add_f32_e32 v0, v170, v0
	v_add_f32_e32 v0, v171, v0
	v_add_f32_e32 v0, v172, v0
	v_add_f32_e32 v0, v173, v0
	v_add_f32_e32 v0, v174, v0
	v_add_f32_e32 v0, v175, v0
	v_add_f32_e32 v0, v176, v0
	v_add_f32_e32 v0, v177, v0
	v_add_f32_e32 v0, v178, v0
	v_add_f32_e32 v0, v179, v0
	v_add_f32_e32 v0, v180, v0
	v_add_f32_e32 v0, v181, v0
	v_add_f32_e32 v0, v182, v0
	v_add_f32_e32 v0, v183, v0
	v_add_f32_e32 v0, v184, v0
	v_add_f32_e32 v0, v185, v0
	v_add_f32_e32 v0, v186, v0
	v_add_f32_e32 v0, v187, v0
	v_add_f32_e32 v0, v188, v0
	v_add_f32_e32 v0, v189, v0
	v_add_f32_e32 v0, v190, v0
	v_add_f32_e32 v0, v191, v0
	v_add_f32_e32 v0, v158, v0
	v_add_f32_e32 v0, v159, v0
	v_add_f32_e32 v0, v160, v0
	v_add_f32_e32 v0, v161, v0
	v_add_f32_e32 v0, v164, v0
	v_add_f32_e32 v0, v165, v0
	v_add_f32_e32 v0, v166, v0
	v_add_f32_e32 v0, v167, v0
.LBB0_533:
	v_add_f32_e32 v157, v157, v0
	ds_read2_b64 v[212:215], v224 offset0:32 offset1:34
	ds_read2_b64 v[216:219], v225 offset1:2
	v_cvt_pk_bf16_f32 v220, v168, v169
	v_cvt_pk_bf16_f32 v221, v170, v171
	v_cvt_pk_bf16_f32 v222, v172, v173
	v_cvt_pk_bf16_f32 v223, v174, v175
	s_add_i32 s12, s12, 3
	s_waitcnt lgkmcnt(1)
	v_mfma_f32_32x32x16_bf16 v[16:31], v[212:215], v[220:223], v[16:31]
	ds_read2_b64 v[212:215], v224 offset0:36 offset1:38
	s_waitcnt lgkmcnt(1)
	v_mfma_f32_32x32x16_bf16 v[32:47], v[216:219], v[220:223], v[32:47]
	ds_read2_b64 v[216:219], v225 offset0:4 offset1:6
	v_cvt_pk_bf16_f32 v220, v176, v177
	v_cvt_pk_bf16_f32 v221, v178, v179
	v_cvt_pk_bf16_f32 v222, v180, v181
	v_cvt_pk_bf16_f32 v223, v182, v183
	s_nop 0
	s_waitcnt lgkmcnt(1)
	v_mfma_f32_32x32x16_bf16 v[16:31], v[212:215], v[220:223], v[16:31]
	ds_read2_b64 v[212:215], v224 offset0:40 offset1:42
	s_waitcnt lgkmcnt(1)
	v_mfma_f32_32x32x16_bf16 v[32:47], v[216:219], v[220:223], v[32:47]
	ds_read2_b64 v[216:219], v225 offset0:8 offset1:10
	v_cvt_pk_bf16_f32 v220, v184, v185
	v_cvt_pk_bf16_f32 v221, v186, v187
	v_cvt_pk_bf16_f32 v222, v188, v189
	v_cvt_pk_bf16_f32 v223, v190, v191
	s_nop 0
	s_waitcnt lgkmcnt(1)
	v_mfma_f32_32x32x16_bf16 v[16:31], v[212:215], v[220:223], v[16:31]
	ds_read2_b64 v[212:215], v224 offset0:44 offset1:46
	s_waitcnt lgkmcnt(1)
	v_mfma_f32_32x32x16_bf16 v[32:47], v[216:219], v[220:223], v[32:47]
	ds_read2_b64 v[216:219], v225 offset0:12 offset1:14
	s_waitcnt vmcnt(0)
	ds_write_b128 v150, v[104:107] offset:13312
	ds_write_b128 v151, v[108:111] offset:13312
	ds_write_b128 v152, v[112:115] offset:13312
	v_cvt_pk_bf16_f32 v220, v158, v159
	v_cvt_pk_bf16_f32 v221, v160, v161
	v_cvt_pk_bf16_f32 v222, v164, v165
	v_cvt_pk_bf16_f32 v223, v166, v167
	s_cmp_ge_u32 s12, s10
	s_waitcnt lgkmcnt(4)
	v_mfma_f32_32x32x16_bf16 v[16:31], v[212:215], v[220:223], v[16:31]
	s_waitcnt lgkmcnt(3)
	v_mfma_f32_32x32x16_bf16 v[32:47], v[216:219], v[220:223], v[32:47]
	ds_write2_b64 v226, v[116:117], v[118:119] offset1:1
	ds_write2_b64 v227, v[120:121], v[122:123] offset1:1
	s_waitcnt lgkmcnt(0)
	s_barrier
	s_cbranch_scc1 .LBB0_535
	global_load_dwordx4 v[104:107], v146, s[24:25]
	global_load_dwordx4 v[108:111], v144, s[24:25]
	global_load_dwordx4 v[112:115], v142, s[24:25]
	global_load_dwordx4 v[116:119], v140, s[26:27] offset:384
	global_load_dwordx4 v[120:123], v140, s[28:29] offset:384
; DI void attn_item(const Params& p, int item, char* smem) {
;     ...
;   auto tile_compute = [&](int cur) {
;     const u16* Kc = Ks + cur * 64 * KSL;
;     const u16* Vc = Vs + cur * 64 * VSL;
;     f32x16 p0, p1;
; #pragma unroll
;     for (int i = 0; i < 16; ++i) { p0[i] = 0.f; p1[i] = 0.f; }
; #pragma unroll
;     for (int d0 = 0; d0 < 6; ++d0) {
;       const bf16x8 a0 = *(const bf16x8*)(Kc + r32 * KSL + d0 * 16 + hi * 8);
;       const bf16x8 a1 = *(const bf16x8*)(Kc + (32 + r32) * KSL + d0 * 16 + hi * 8);
;       p0 = __builtin_amdgcn_mfma_f32_32x32x16_bf16(a0, qr[d0], p0, 0, 0, 0);
;       p1 = __builtin_amdgcn_mfma_f32_32x32x16_bf16(a1, qr[d0], p1, 0, 0, 0);
;     }
;     float mx = p0[0];
; #pragma unroll
;     for (int i = 1; i < 16; ++i) mx = fmaxf(mx, p0[i]);
; #pragma unroll
;     for (int i = 0; i < 16; ++i) mx = fmaxf(mx, p1[i]);
;     { auto rr = __builtin_amdgcn_permlane32_swap(__float_as_uint(mx), __float_as_uint(mx), false, false);
;       mx = fmaxf(__uint_as_float(rr[0]), __uint_as_float(rr[1])); }
;     if (!__all(mx - mrun <= 8.f)) {
;       const float mn = fmaxf(mrun, mx);
;       const float alpha = __builtin_amdgcn_exp2f(mrun - mn);
;       mrun = mn; lrun *= alpha;
; #pragma unroll
;       for (int i = 0; i < 16; ++i) { o0[i] *= alpha; o1[i] *= alpha; }
;     }
.LBB0_535:
	ds_read_b128 v[164:167], v154 offset:13312
	ds_read_b128 v[168:171], v154 offset:13344
	ds_read_b128 v[172:175], v154 offset:13376
	ds_read_b128 v[176:179], v154 offset:13408
	ds_read_b128 v[180:183], v154 offset:13440
	ds_read_b128 v[184:187], v154 offset:13472
	ds_read_b128 v[188:191], v154 offset:19968
	ds_read_b128 v[158:161], v154 offset:20000
	ds_read_b128 v[192:195], v154 offset:20032
	ds_read_b128 v[212:215], v154 offset:20064
	ds_read_b128 v[216:219], v154 offset:20096
	ds_read_b128 v[10:13], v154 offset:20128
	s_waitcnt lgkmcnt(11)
	v_mfma_f32_32x32x16_bf16 v[64:79], v[164:167], v[80:83], v[196:211]
	s_waitcnt lgkmcnt(10)
	v_mfma_f32_32x32x16_bf16 v[64:79], v[168:171], v[84:87], v[64:79]
	s_waitcnt lgkmcnt(9)
	v_mfma_f32_32x32x16_bf16 v[64:79], v[172:175], v[88:91], v[64:79]
	s_waitcnt lgkmcnt(8)
	v_mfma_f32_32x32x16_bf16 v[64:79], v[176:179], v[92:95], v[64:79]
	s_waitcnt lgkmcnt(7)
	v_mfma_f32_32x32x16_bf16 v[64:79], v[180:183], v[96:99], v[64:79]
	s_waitcnt lgkmcnt(6)
	v_mfma_f32_32x32x16_bf16 v[64:79], v[184:187], v[100:103], v[64:79]
	s_waitcnt lgkmcnt(5)
	v_mfma_f32_32x32x16_bf16 v[48:63], v[188:191], v[80:83], v[196:211]
	s_waitcnt lgkmcnt(4)
	v_mfma_f32_32x32x16_bf16 v[48:63], v[158:161], v[84:87], v[48:63]
	s_nop 7
	v_exp_f32_e32 v168, v64
	v_exp_f32_e32 v169, v65
	v_exp_f32_e32 v170, v66
	v_exp_f32_e32 v171, v67
	v_exp_f32_e32 v172, v68
	v_exp_f32_e32 v173, v69
	v_exp_f32_e32 v174, v70
	v_exp_f32_e32 v175, v71
	s_waitcnt lgkmcnt(3)
	v_mfma_f32_32x32x16_bf16 v[48:63], v[192:195], v[88:91], v[48:63]
	s_waitcnt lgkmcnt(2)
	v_mfma_f32_32x32x16_bf16 v[48:63], v[212:215], v[92:95], v[48:63]
	v_exp_f32_e32 v176, v72
	v_exp_f32_e32 v177, v73
	v_exp_f32_e32 v178, v74
	v_exp_f32_e32 v179, v75
	v_exp_f32_e32 v180, v76
	v_exp_f32_e32 v181, v77
	v_exp_f32_e32 v182, v78
	v_exp_f32_e32 v183, v79
	s_waitcnt lgkmcnt(1)
	v_mfma_f32_32x32x16_bf16 v[48:63], v[216:219], v[96:99], v[48:63]
	s_waitcnt lgkmcnt(0)
	v_mfma_f32_32x32x16_bf16 v[48:63], v[10:13], v[100:103], v[48:63]
	v_add_f32_e32 v0, v168, v169
	v_add_f32_e32 v0, v170, v0
	v_add_f32_e32 v0, v171, v0
	v_add_f32_e32 v0, v172, v0
	v_add_f32_e32 v0, v173, v0
	v_add_f32_e32 v0, v174, v0
	v_add_f32_e32 v0, v175, v0
	v_add_f32_e32 v0, v176, v0
	v_add_f32_e32 v0, v177, v0
	v_add_f32_e32 v0, v178, v0
	v_add_f32_e32 v0, v179, v0
	v_add_f32_e32 v0, v180, v0
	v_add_f32_e32 v0, v181, v0
	v_add_f32_e32 v0, v182, v0
	v_add_f32_e32 v0, v183, v0
	v_exp_f32_e32 v184, v48
	v_exp_f32_e32 v185, v49
	v_exp_f32_e32 v186, v50
	v_exp_f32_e32 v187, v51
	v_exp_f32_e32 v188, v52
	v_exp_f32_e32 v189, v53
	v_exp_f32_e32 v190, v54
	v_exp_f32_e32 v191, v55
	v_exp_f32_e32 v158, v56
	v_exp_f32_e32 v159, v57
	v_exp_f32_e32 v160, v58
	v_exp_f32_e32 v161, v59
	v_exp_f32_e32 v164, v60
	v_exp_f32_e32 v165, v61
	v_exp_f32_e32 v166, v62
	v_exp_f32_e32 v167, v63
	v_add_f32_e32 v0, v184, v0
	v_add_f32_e32 v0, v185, v0
	v_add_f32_e32 v0, v186, v0
	v_add_f32_e32 v0, v187, v0
	v_add_f32_e32 v0, v188, v0
	v_add_f32_e32 v0, v189, v0
	v_add_f32_e32 v0, v190, v0
	v_add_f32_e32 v0, v191, v0
	v_add_f32_e32 v0, v158, v0
	v_add_f32_e32 v0, v159, v0
	v_add_f32_e32 v0, v160, v0
	v_add_f32_e32 v0, v161, v0
	v_add_f32_e32 v0, v164, v0
	v_add_f32_e32 v0, v165, v0
	v_add_f32_e32 v0, v166, v0
	v_add_f32_e32 v0, v167, v0
	v_cmp_ge_f32_e32 vcc, s98, v0
	s_cmp_eq_u64 vcc, exec
	s_cbranch_scc1 .LBB0_537
	v_max_f32_e32 v10, v64, v65
	v_max3_f32 v10, v10, v66, v67
	v_max3_f32 v10, v10, v68, v69
	v_max3_f32 v10, v10, v70, v71
	v_max3_f32 v10, v10, v72, v73
	v_max3_f32 v10, v10, v74, v75
	v_max3_f32 v10, v10, v76, v77
	v_max3_f32 v10, v10, v78, v79
	v_max3_f32 v10, v10, v48, v49
	v_max3_f32 v10, v10, v50, v51
	v_max3_f32 v10, v10, v52, v53
	v_max3_f32 v10, v10, v54, v55
	v_max3_f32 v10, v10, v56, v57
	v_max3_f32 v10, v10, v58, v59
	v_max3_f32 v10, v10, v60, v61
	v_max3_f32 v10, v10, v62, v63
	v_mov_b32_e32 v11, v10
	s_nop 1
	v_permlane32_swap_b32_e32 v10, v11
	v_max_f32_e32 v10, v10, v11
	v_max_f32_e32 v11, s99, v10
	v_max_f32_e32 v10, 0, v11
	s_mov_b32 s98, 0x46000000
	v_exp_f32_e64 v10, -v10
	s_mov_b32 s99, 0
	v_sub_f32_e32 v196, v196, v11
	v_mul_f32_e32 v157, v157, v10
	v_pk_mul_f32 v[46:47], v[46:47], v[10:11] op_sel_hi:[1,0]
	v_pk_mul_f32 v[44:45], v[44:45], v[10:11] op_sel_hi:[1,0]
	v_pk_mul_f32 v[42:43], v[42:43], v[10:11] op_sel_hi:[1,0]
	v_pk_mul_f32 v[40:41], v[40:41], v[10:11] op_sel_hi:[1,0]
	v_pk_mul_f32 v[38:39], v[38:39], v[10:11] op_sel_hi:[1,0]
	v_pk_mul_f32 v[36:37], v[36:37], v[10:11] op_sel_hi:[1,0]
	v_pk_mul_f32 v[34:35], v[34:35], v[10:11] op_sel_hi:[1,0]
	v_pk_mul_f32 v[32:33], v[32:33], v[10:11] op_sel_hi:[1,0]
	v_pk_mul_f32 v[30:31], v[30:31], v[10:11] op_sel_hi:[1,0]
	v_pk_mul_f32 v[28:29], v[28:29], v[10:11] op_sel_hi:[1,0]
	v_pk_mul_f32 v[26:27], v[26:27], v[10:11] op_sel_hi:[1,0]
	v_pk_mul_f32 v[24:25], v[24:25], v[10:11] op_sel_hi:[1,0]
	v_pk_mul_f32 v[22:23], v[22:23], v[10:11] op_sel_hi:[1,0]
	v_pk_mul_f32 v[20:21], v[20:21], v[10:11] op_sel_hi:[1,0]
	v_pk_mul_f32 v[18:19], v[18:19], v[10:11] op_sel_hi:[1,0]
	v_pk_mul_f32 v[16:17], v[16:17], v[10:11] op_sel_hi:[1,0]
	v_mov_b32_e32 v197, v196
	v_mov_b32_e32 v198, v196
	v_mov_b32_e32 v199, v196
	v_mov_b32_e32 v200, v196
	v_mov_b32_e32 v201, v196
	v_mov_b32_e32 v202, v196
; DI void attn_item(const Params& p, int item, char* smem) {
;     ...
;     if (!__all(mx - mrun <= 8.f)) {
;       const float mn = fmaxf(mrun, mx);
;       const float alpha = __builtin_amdgcn_exp2f(mrun - mn);
;       mrun = mn; lrun *= alpha;
; #pragma unroll
;       for (int i = 0; i < 16; ++i) { o0[i] *= alpha; o1[i] *= alpha; }
;     }
;     float ps = 0.f;
; #pragma unroll
;     for (int i = 0; i < 16; ++i) { p0[i] = __builtin_amdgcn_exp2f(p0[i] - mrun); ps += p0[i]; }
; #pragma unroll
;     for (int i = 0; i < 16; ++i) { p1[i] = __builtin_amdgcn_exp2f(p1[i] - mrun); ps += p1[i]; }
;     lrun += ps;
;     pv_step(o0, o1, Vc, r32, 0 + hi * 4, pack8<0>(p0));
;     pv_step(o0, o1, Vc, r32, 16 + hi * 4, pack8<8>(p0));
;     pv_step(o0, o1, Vc, r32, 32 + hi * 4, pack8<0>(p1));
;     pv_step(o0, o1, Vc, r32, 48 + hi * 4, pack8<8>(p1));
;     ...
;   for (int kt = 0; kt < nkt; kt += 2) {
;     if (kt + 2 < nkt) gload(b, kt + 2);
;     tile_compute(0);
;     lstore(a, 1);
;     __syncthreads();
;     if (kt + 3 < nkt) gload(a, kt + 3);
;     tile_compute(1);
;     if (kt + 2 < nkt) lstore(b, 0);
;     __syncthreads();
;   }
	v_mov_b32_e32 v203, v196
	v_mov_b32_e32 v204, v196
	v_mov_b32_e32 v205, v196
	v_mov_b32_e32 v206, v196
	v_mov_b32_e32 v207, v196
	v_mov_b32_e32 v208, v196
	v_mov_b32_e32 v209, v196
	v_mov_b32_e32 v210, v196
	v_mov_b32_e32 v211, v196
	v_sub_f32_e32 v64, v64, v11
	v_sub_f32_e32 v65, v65, v11
	v_sub_f32_e32 v66, v66, v11
	v_sub_f32_e32 v67, v67, v11
	v_sub_f32_e32 v68, v68, v11
	v_sub_f32_e32 v69, v69, v11
	v_sub_f32_e32 v70, v70, v11
	v_sub_f32_e32 v71, v71, v11
	v_sub_f32_e32 v72, v72, v11
	v_sub_f32_e32 v73, v73, v11
	v_sub_f32_e32 v74, v74, v11
	v_sub_f32_e32 v75, v75, v11
	v_sub_f32_e32 v76, v76, v11
	v_sub_f32_e32 v77, v77, v11
	v_sub_f32_e32 v78, v78, v11
	v_sub_f32_e32 v79, v79, v11
	v_sub_f32_e32 v48, v48, v11
	v_sub_f32_e32 v49, v49, v11
	v_sub_f32_e32 v50, v50, v11
	v_sub_f32_e32 v51, v51, v11
	v_sub_f32_e32 v52, v52, v11
	v_sub_f32_e32 v53, v53, v11
	v_sub_f32_e32 v54, v54, v11
	v_sub_f32_e32 v55, v55, v11
	v_sub_f32_e32 v56, v56, v11
	v_sub_f32_e32 v57, v57, v11
	v_sub_f32_e32 v58, v58, v11
	v_sub_f32_e32 v59, v59, v11
	v_sub_f32_e32 v60, v60, v11
	v_sub_f32_e32 v61, v61, v11
	v_sub_f32_e32 v62, v62, v11
	v_sub_f32_e32 v63, v63, v11
	v_exp_f32_e32 v168, v64
	v_exp_f32_e32 v169, v65
	v_exp_f32_e32 v170, v66
	v_exp_f32_e32 v171, v67
	v_exp_f32_e32 v172, v68
	v_exp_f32_e32 v173, v69
	v_exp_f32_e32 v174, v70
	v_exp_f32_e32 v175, v71
	v_exp_f32_e32 v176, v72
	v_exp_f32_e32 v177, v73
	v_exp_f32_e32 v178, v74
	v_exp_f32_e32 v179, v75
	v_exp_f32_e32 v180, v76
	v_exp_f32_e32 v181, v77
	v_exp_f32_e32 v182, v78
	v_exp_f32_e32 v183, v79
	v_exp_f32_e32 v184, v48
	v_exp_f32_e32 v185, v49
	v_exp_f32_e32 v186, v50
	v_exp_f32_e32 v187, v51
	v_exp_f32_e32 v188, v52
	v_exp_f32_e32 v189, v53
	v_exp_f32_e32 v190, v54
	v_exp_f32_e32 v191, v55
	v_exp_f32_e32 v158, v56
	v_exp_f32_e32 v159, v57
	v_exp_f32_e32 v160, v58
	v_exp_f32_e32 v161, v59
	v_exp_f32_e32 v164, v60
	v_exp_f32_e32 v165, v61
	v_exp_f32_e32 v166, v62
	v_exp_f32_e32 v167, v63
	v_add_f32_e32 v0, v168, v169
	v_add_f32_e32 v0, v170, v0
	v_add_f32_e32 v0, v171, v0
	v_add_f32_e32 v0, v172, v0
	v_add_f32_e32 v0, v173, v0
	v_add_f32_e32 v0, v174, v0
	v_add_f32_e32 v0, v175, v0
	v_add_f32_e32 v0, v176, v0
	v_add_f32_e32 v0, v177, v0
	v_add_f32_e32 v0, v178, v0
	v_add_f32_e32 v0, v179, v0
	v_add_f32_e32 v0, v180, v0
	v_add_f32_e32 v0, v181, v0
	v_add_f32_e32 v0, v182, v0
	v_add_f32_e32 v0, v183, v0
	v_add_f32_e32 v0, v184, v0
	v_add_f32_e32 v0, v185, v0
	v_add_f32_e32 v0, v186, v0
	v_add_f32_e32 v0, v187, v0
	v_add_f32_e32 v0, v188, v0
	v_add_f32_e32 v0, v189, v0
	v_add_f32_e32 v0, v190, v0
	v_add_f32_e32 v0, v191, v0
	v_add_f32_e32 v0, v158, v0
	v_add_f32_e32 v0, v159, v0
	v_add_f32_e32 v0, v160, v0
	v_add_f32_e32 v0, v161, v0
	v_add_f32_e32 v0, v164, v0
	v_add_f32_e32 v0, v165, v0
	v_add_f32_e32 v0, v166, v0
	v_add_f32_e32 v0, v167, v0
.LBB0_537:
	v_add_f32_e32 v157, v157, v0
	ds_read2_b64 v[212:215], v228 offset0:64 offset1:66
	ds_read2_b64 v[216:219], v229 offset0:96 offset1:98
	v_cvt_pk_bf16_f32 v220, v168, v169
	v_cvt_pk_bf16_f32 v221, v170, v171
	v_cvt_pk_bf16_f32 v222, v172, v173
	v_cvt_pk_bf16_f32 v223, v174, v175
	s_andn2_b64 vcc, exec, s[6:7]
	s_waitcnt lgkmcnt(1)
	v_mfma_f32_32x32x16_bf16 v[32:47], v[212:215], v[220:223], v[32:47]
	ds_read2_b64 v[212:215], v228 offset0:68 offset1:70
	s_waitcnt lgkmcnt(1)
	v_mfma_f32_32x32x16_bf16 v[16:31], v[216:219], v[220:223], v[16:31]
	ds_read2_b64 v[216:219], v229 offset0:100 offset1:102
	v_cvt_pk_bf16_f32 v220, v176, v177
	v_cvt_pk_bf16_f32 v221, v178, v179
	v_cvt_pk_bf16_f32 v222, v180, v181
	v_cvt_pk_bf16_f32 v223, v182, v183
	s_nop 0
	s_waitcnt lgkmcnt(1)
	v_mfma_f32_32x32x16_bf16 v[32:47], v[212:215], v[220:223], v[32:47]
	ds_read2_b64 v[212:215], v228 offset0:72 offset1:74
	s_waitcnt lgkmcnt(1)
	v_mfma_f32_32x32x16_bf16 v[16:31], v[216:219], v[220:223], v[16:31]
	ds_read2_b64 v[216:219], v229 offset0:104 offset1:106
	v_cvt_pk_bf16_f32 v220, v184, v185
	v_cvt_pk_bf16_f32 v221, v186, v187
	v_cvt_pk_bf16_f32 v222, v188, v189
	v_cvt_pk_bf16_f32 v223, v190, v191
	s_nop 0
	s_waitcnt lgkmcnt(1)
	v_mfma_f32_32x32x16_bf16 v[32:47], v[212:215], v[220:223], v[32:47]
	ds_read2_b64 v[212:215], v228 offset0:76 offset1:78
	s_waitcnt lgkmcnt(1)
	v_mfma_f32_32x32x16_bf16 v[16:31], v[216:219], v[220:223], v[16:31]
	ds_read2_b64 v[216:219], v229 offset0:108 offset1:110
	v_cvt_pk_bf16_f32 v220, v158, v159
	v_cvt_pk_bf16_f32 v221, v160, v161
	v_cvt_pk_bf16_f32 v222, v164, v165
	v_cvt_pk_bf16_f32 v223, v166, v167
	s_nop 0
	s_waitcnt lgkmcnt(1)
	v_mfma_f32_32x32x16_bf16 v[32:47], v[212:215], v[220:223], v[32:47]
	s_waitcnt lgkmcnt(0)
	v_mfma_f32_32x32x16_bf16 v[16:31], v[216:219], v[220:223], v[16:31]
	s_cbranch_vccnz .LBB0_539
	ds_write_b128 v150, v[124:127]
	ds_write_b128 v151, v[128:131]
	ds_write_b128 v152, v[132:135]
	ds_write2_b64 v139, v[2:3], v[4:5] offset1:1
	ds_write2_b64 v230, v[6:7], v[8:9] offset1:1
.LBB0_539:
	v_lshl_add_u64 v[140:141], v[140:141], 0, s[50:51]
	v_lshl_add_u64 v[142:143], v[142:143], 0, s[66:67]
	v_lshl_add_u64 v[144:145], v[144:145], 0, s[66:67]
	s_andn2_b64 vcc, exec, s[4:5]
	v_lshl_add_u64 v[146:147], v[146:147], 0, s[66:67]
	s_waitcnt lgkmcnt(0)
	s_barrier
	s_cbranch_vccz .LBB0_518
	s_mov_b32 s12, s11
	s_branch .LBB0_529
